# grid barrier leader path: release the XCD generation word before invalidating own L1 (instruction moved, byte count of each site unchanged)
# baseline (speedup 1.0000x reference)
.LBB0_171:
	s_or_b64 exec, exec, s[4:5]
	s_mov_b64 s[4:5], exec
	v_mbcnt_lo_u32_b32 v2, s4, 0
	v_mbcnt_hi_u32_b32 v2, s5, v2
	v_cmp_eq_u32_e32 vcc, 0, v2
	s_nop 0
	s_and_saveexec_b64 s[6:7], vcc
	s_cbranch_execz .LBB0_173
	s_bcnt1_i32_b64 s4, s[4:5]
	v_mov_b32_e32 v2, 0x2000
	v_mov_b32_e32 v3, s4
	global_atomic_add v2, v3, s[2:3] offset:1024

.LBB0_263:
	s_or_b64 exec, exec, s[26:27]
	s_mov_b64 s[26:27], exec
	v_mbcnt_lo_u32_b32 v0, s26, 0
	v_mbcnt_hi_u32_b32 v0, s27, v0
	v_cmp_eq_u32_e32 vcc, 0, v0
	s_nop 0
	s_and_saveexec_b64 s[28:29], vcc
	s_cbranch_execz .LBB0_265
	s_bcnt1_i32_b64 s2, s[26:27]
	v_mov_b32_e32 v0, s2
	v_readlane_b32 s2, v253, 52
	v_readlane_b32 s3, v253, 53
	s_nop 4
	global_atomic_add v199, v0, s[2:3]
